# attention K/V staging by LDS-DMA with the chunk swizzle moved to the source address (no per-item ds_write ladder)
# baseline (speedup 1.0000x reference)
; __device__ __forceinline__ void attn_phase(const Params& p, LAS unsigned char* lds) {
;     ...
;     const int ri = w >> 2, qb = w & 3, q0 = qb * 16, kc0 = min(max(q0 - 8, 0), 32);
;     const int kperm = 8 * (fr >> 2) + (fr & 3);
;     for (;;) {
;         __syncthreads();
;         if (tid == 0) slot[0] = __hip_atomic_fetch_add(ctr, 1u, __ATOMIC_RELAXED, __HIP_MEMORY_SCOPE_AGENT);
;         __syncthreads();
;         const int item = (int)slot[0];
;         if (item >= 1024) break;
;         const int b = item >> 7, h = (item >> 4) & 7, r0 = (item & 15) * 2, R0 = min(max(r0 - 4, 0), 24);
;         const int r = r0 + ri, rs = min(max(r - 4, 0), 24), j0 = rs - R0;
;         const int tq = b * SEQ + r * 64 + q0 + fr;
;         const bf16_t* qp = QH + ((size_t)(b * 8 + h) * SEQ + r * 64 + q0 + fr) * 64 + fq * 8;
;         const bf16x8 qf0 = *(const bf16x8*)qp, qf1 = *(const bf16x8*)(qp + 32);
;         for (int u = tid; u < 465; u += NTHREADS) rp[u] = p.rpb[h * 465 + u] * 1.4426950408889634f;
;         { const int t = tid >> 3, c = tid & 7; const unsigned dstk = (unsigned)(t * 128 + ((c ^ (((t >> 1) & 1) | (((t >> 3) & 3) << 1))) << 4)), dstv = (unsigned)(t * 128 + ((c ^ ((t >> 1) & 7)) << 4));
;           u32x4 kv[9], vv[9];
; #pragma unroll
;           for (int j = 0; j < 9; ++j) { const int srow = min(R0 + j, 31);
;               kv[j] = *(const u32x4*)(KH + ((size_t)(b * 8 + h) * SEQ + srow * 64 + t) * 64 + c * 8);
;               vv[j] = *(const u32x4*)(VTA + ((size_t)((b * 8 + h) * 32 + srow) * 64 + t) * 64 + c * 8); }
;     ...
;         const int qc = q0 + fr, cs0 = min(max(qc - 8, 0), 48);
;         float madd[2][4]; int dco[2][4];
; #pragma unroll
;         for (int t = 0; t < 2; ++t)
; #pragma unroll
;             for (int j = 0; j < 4; ++j) { const int kc = kc0 + 8 * fq + 4 * t + j; madd[t][j] = ((kc >= cs0) && (kc < cs0 + 16)) ? 0.f : -1e30f; dco[t][j] = min(max(kc - qc, -15), 15); }
.LBB0_335:
	s_waitcnt lgkmcnt(0)
	s_add_u32 s12, s34, 0x180000
	s_addc_u32 s13, s35, 0
	v_readfirstlane_b32 s0, v170
	s_add_u32 s14, s34, 0x83800
	s_addc_u32 s15, s35, 0
	s_lshr_b32 s10, s0, 8
	s_lshr_b32 s0, s0, 2
	s_and_b32 s0, s0, 48
	v_sub_u32_e64 v0, s0, 8 clamp
	v_min_u32_e32 v4, 32, v0
	v_lshlrev_b32_e32 v0, 1, v170
	v_and_b32_e32 v1, 3, v170
	v_mov_b32_e32 v31, 0
	v_lshlrev_b32_e32 v30, 1, v130
	v_and_or_b32 v5, v0, 24, v1
	v_or_b32_e32 v28, s0, v131
	v_lshl_add_u64 v[0:1], s[34:35], 0, v[30:31]
	s_mov_b64 s[0:1], 0x5f00000
	v_lshl_add_u64 v[32:33], v[0:1], 0, s[0:1]
	v_and_b32_e32 v1, 7, v170
	v_bfe_u32 v2, v170, 4, 1
	v_and_b32_e32 v3, 6, v133
	v_bitop3_b32 v2, v2, v1, v3 bitop3:0x36
	v_lshlrev_b32_e32 v6, 4, v2
	v_xor_b32_e32 v2, v172, v170
	v_lshlrev_b32_e32 v2, 4, v2
	v_lshlrev_b32_e32 v30, 4, v1
	v_lshlrev_b32_e32 v0, 7, v128
	v_and_b32_e32 v7, 0x70, v2
	v_mov_b32_e32 v244, v6
	v_mov_b32_e32 v245, 0
	v_lshl_add_u64 v[2:3], s[34:35], 0, v[244:245]
	s_mov_b64 s[4:5], 0x6f00000
	v_mov_b32_e32 v1, v31
	v_lshl_add_u64 v[34:35], v[2:3], 0, s[4:5]
	v_lshl_add_u64 v[2:3], s[34:35], 0, v[0:1]
	v_mov_b32_e32 v246, v7
	v_mov_b32_e32 v247, 0
	v_lshl_add_u64 v[2:3], v[2:3], 0, v[246:247]
	s_mov_b64 s[4:5], 0x7f00000
	v_add_u32_e32 v1, v4, v5
	v_lshl_add_u64 v[36:37], v[2:3], 0, s[4:5]
	v_lshrrev_b32_e32 v3, 2, v1
	v_bfe_u32 v2, v170, 1, 1
	v_and_b32_e32 v3, 6, v3
	v_bitop3_b32 v5, v3, v129, v2 bitop3:0x36
	v_lshlrev_b32_e32 v39, 4, v5
	v_or_b32_e32 v5, 4, v129
	s_add_i32 s4, 0, 0x12000
	v_bitop3_b32 v2, v3, v5, v2 bitop3:0x36
	v_add_u32_e32 v3, v4, v130
	v_lshrrev_b32_e32 v4, 3, v4
	v_add3_u32 v29, 0, v0, v6
	v_add3_u32 v38, s4, v0, v7
	v_lshrrev_b32_e32 v0, 1, v170
	v_lshlrev_b32_e32 v40, 4, v2
	v_sub_u32_e64 v2, v28, 8 clamp
	v_add_u32_e32 v4, v4, v129
	v_min_u32_e32 v2, 48, v2
	v_bitop3_b32 v0, v4, v0, 7 bitop3:0x78
	v_add_u32_e32 v5, 16, v2
	v_lshlrev_b32_e32 v6, 7, v131
	v_lshlrev_b32_e32 v0, 4, v0
	s_add_i32 s6, 0, 0x24000
	v_add3_u32 v41, s4, v6, v0
	v_lshl_add_u32 v42, v170, 2, s6
	v_cmp_ge_u32_e32 vcc, v3, v2
	v_cmp_lt_u32_e64 s[6:7], v3, v5
	v_sub_u32_e32 v6, v3, v28
	v_mov_b32_e32 v4, 0xf149f2ca
	s_and_b64 s[6:7], vcc, s[6:7]
	v_med3_i32 v46, v6, -15, 15
	v_or_b32_e32 v6, 1, v3
	v_cndmask_b32_e64 v45, v4, 0, s[6:7]
	v_cmp_ge_u32_e32 vcc, v6, v2
	v_cmp_lt_u32_e64 s[6:7], v6, v5
	v_sub_u32_e32 v6, v6, v28
	s_and_b64 s[6:7], vcc, s[6:7]
	v_med3_i32 v48, v6, -15, 15
	v_or_b32_e32 v6, 2, v3
	v_cndmask_b32_e64 v47, v4, 0, s[6:7]
	v_cmp_ge_u32_e32 vcc, v6, v2
	v_cmp_lt_u32_e64 s[6:7], v6, v5
	v_sub_u32_e32 v6, v6, v28
	s_and_b64 s[6:7], vcc, s[6:7]
	v_med3_i32 v50, v6, -15, 15
	v_or_b32_e32 v6, 3, v3
	v_cndmask_b32_e64 v49, v4, 0, s[6:7]
	v_cmp_ge_u32_e32 vcc, v6, v2
	v_cmp_lt_u32_e64 s[6:7], v6, v5
	v_sub_u32_e32 v6, v6, v28
	s_and_b64 s[6:7], vcc, s[6:7]
	v_med3_i32 v52, v6, -15, 15
	v_or_b32_e32 v6, 4, v3
	v_cndmask_b32_e64 v51, v4, 0, s[6:7]
	v_cmp_ge_u32_e32 vcc, v6, v2
	v_cmp_lt_u32_e64 s[6:7], v6, v5
	v_sub_u32_e32 v6, v6, v28
	s_and_b64 s[6:7], vcc, s[6:7]
	v_med3_i32 v54, v6, -15, 15
	v_or_b32_e32 v6, 5, v3
	v_cndmask_b32_e64 v53, v4, 0, s[6:7]
	v_cmp_ge_u32_e32 vcc, v6, v2
	v_cmp_lt_u32_e64 s[6:7], v6, v5
	v_sub_u32_e32 v6, v6, v28
	s_and_b64 s[6:7], vcc, s[6:7]
	v_med3_i32 v56, v6, -15, 15
	v_or_b32_e32 v6, 6, v3
	v_cndmask_b32_e64 v55, v4, 0, s[6:7]
	v_cmp_ge_u32_e32 vcc, v6, v2
	v_cmp_lt_u32_e64 s[6:7], v6, v5
	s_and_b64 s[6:7], vcc, s[6:7]
	v_or_b32_e32 v3, 7, v3
	v_lshlrev_b32_e32 v0, 2, v129
	v_cndmask_b32_e64 v57, v4, 0, s[6:7]
	v_cmp_ge_u32_e32 vcc, v3, v2
	v_cmp_lt_u32_e64 s[6:7], v3, v5
	s_movk_i32 s0, 0x1d1
	v_sub_u32_e32 v6, v6, v28
	s_and_b64 s[6:7], vcc, s[6:7]
	v_sub_u32_e32 v2, v3, v28
	v_lshlrev_b32_e32 v30, 1, v0
	v_mbcnt_lo_u32_b32 v0, -1, 0
	v_cmp_gt_u32_e64 s[0:1], s0, v170
	s_mov_b32 s17, 0
	v_cmp_eq_u32_e64 s[4:5], 0, v129
	v_add_u32_e32 v43, 0x10000, v29
	v_add_u32_e32 v44, 0x10000, v38
	s_mov_b32 s11, 0xf149f2ca
	v_med3_i32 v58, v6, -15, 15
	v_cndmask_b32_e64 v59, v4, 0, s[6:7]
	v_med3_i32 v60, v2, -15, 15
	v_lshl_add_u32 v61, v1, 7, 0
	s_add_i32 s33, 0, 0x24800
	s_movk_i32 s40, 0x3ff
	s_mov_b64 s[6:7], 0xb200400
	s_mov_b32 s41, 0xb200000
	v_mbcnt_hi_u32_b32 v62, -1, v0
	s_and_saveexec_b64 s[98:99], s[58:59]
	s_cbranch_execz .Lattn_pf_a
	v_mov_b32_e32 v243, 1
	global_atomic_add v242, v31, v243, s[14:15] sc0

; #define LAS __attribute__((address_space(3)))
; __device__ __forceinline__ void attn_phase(const Params& p, LAS unsigned char* lds) {
;     ...
;         for (int u = tid; u < 465; u += NTHREADS) rp[u] = p.rpb[h * 465 + u] * 1.4426950408889634f;
;         { const int t = tid >> 3, c = tid & 7; const unsigned dstk = (unsigned)(t * 128 + ((c ^ (((t >> 1) & 1) | (((t >> 3) & 3) << 1))) << 4)), dstv = (unsigned)(t * 128 + ((c ^ ((t >> 1) & 7)) << 4));
;           u32x4 kv[9], vv[9];
; #pragma unroll
;           for (int j = 0; j < 9; ++j) { const int srow = min(R0 + j, 31);
;               kv[j] = *(const u32x4*)(KH + ((size_t)(b * 8 + h) * SEQ + srow * 64 + t) * 64 + c * 8);
;               vv[j] = *(const u32x4*)(VTA + ((size_t)((b * 8 + h) * 32 + srow) * 64 + t) * 64 + c * 8); }
; #pragma unroll
;           for (int j = 0; j < 9; ++j) { *(LAS u32x4*)(Ks + j * 8192 + dstk) = kv[j]; *(LAS u32x4*)(Vs + j * 8192 + dstv) = vv[j]; } }
;         __syncthreads();
.LBB0_345:
	s_or_b64 exec, exec, s[38:39]
	v_sub_u32_e64 v0, s16, 4 clamp
	v_or_b32_e32 v108, s26, v128
	v_readfirstlane_b32 s38, v0
	s_min_u32 s39, s38, 24
	s_lshl_b32 s26, s20, 5
	s_or_b32 s20, s39, s26
	s_ashr_i32 s21, s20, 31
	s_lshl_b64 s[20:21], s[20:21], 13
	v_lshl_add_u64 v[8:9], v[36:37], 0, s[20:21]
	s_or_b32 s20, s39, 1
	s_lshl_b32 s16, s20, 6
	s_or_b32 s20, s20, s26
	s_ashr_i32 s21, s20, 31
	s_lshl_b64 s[20:21], s[20:21], 13
	v_mov_b32_e32 v109, s27
	v_lshl_add_u64 v[20:21], v[36:37], 0, s[20:21]
	s_add_i32 s20, s39, 2
	v_lshl_add_u64 v[16:17], v[108:109], 0, s[16:17]
	s_lshl_b32 s16, s20, 6
	s_or_b32 s20, s20, s26
	s_ashr_i32 s21, s20, 31
	s_lshl_b64 s[20:21], s[20:21], 13
	v_lshl_add_u64 v[64:65], v[36:37], 0, s[20:21]
	s_add_i32 s20, s39, 3
	v_lshl_add_u64 v[24:25], v[108:109], 0, s[16:17]
	s_lshl_b32 s16, s20, 6
	s_or_b32 s20, s20, s26
	s_ashr_i32 s21, s20, 31
	s_lshl_b64 s[20:21], s[20:21], 13
	v_lshl_add_u64 v[72:73], v[36:37], 0, s[20:21]
	s_add_i32 s20, s39, 4
	v_lshl_add_u64 v[68:69], v[108:109], 0, s[16:17]
	s_lshl_b32 s16, s20, 6
	s_or_b32 s20, s20, s26
	s_ashr_i32 s21, s20, 31
	s_lshl_b64 s[20:21], s[20:21], 13
	v_lshl_add_u64 v[80:81], v[36:37], 0, s[20:21]
	s_add_i32 s20, s39, 5
	v_lshl_add_u64 v[76:77], v[108:109], 0, s[16:17]
	s_lshl_b32 s16, s20, 6
	s_or_b32 s20, s20, s26
	s_ashr_i32 s21, s20, 31
	s_lshl_b64 s[20:21], s[20:21], 13
	v_lshl_add_u64 v[88:89], v[36:37], 0, s[20:21]
	s_add_i32 s20, s39, 6
	v_lshl_add_u64 v[84:85], v[108:109], 0, s[16:17]
	s_lshl_b32 s16, s20, 6
	s_or_b32 s20, s20, s26
	s_ashr_i32 s21, s20, 31
	s_lshl_b64 s[20:21], s[20:21], 13
	v_lshl_add_u64 v[96:97], v[36:37], 0, s[20:21]
	s_add_i32 s20, s39, 7
	v_lshl_add_u64 v[92:93], v[108:109], 0, s[16:17]
	s_lshl_b32 s16, s20, 6
	s_or_b32 s20, s20, s26
	s_ashr_i32 s21, s20, 31
	v_lshl_add_u64 v[100:101], v[108:109], 0, s[16:17]
	s_lshl_b64 s[20:21], s[20:21], 13
	s_min_u32 s16, s38, 23
	v_lshl_add_u64 v[104:105], v[36:37], 0, s[20:21]
	s_add_i32 s20, s16, 8
	s_lshl_b32 s16, s20, 6
	s_or_b32 s20, s20, s26
	v_lshl_or_b32 v0, s39, 6, v108
	v_mov_b32_e32 v1, s27
	v_lshl_add_u64 v[108:109], v[108:109], 0, s[16:17]
	s_ashr_i32 s21, s20, 31
	v_lshlrev_b64 v[0:1], 7, v[0:1]
	v_lshlrev_b64 v[16:17], 7, v[16:17]
	v_lshlrev_b64 v[24:25], 7, v[24:25]
	v_lshlrev_b64 v[68:69], 7, v[68:69]
	v_lshlrev_b64 v[76:77], 7, v[76:77]
	v_lshlrev_b64 v[84:85], 7, v[84:85]
	v_lshlrev_b64 v[92:93], 7, v[92:93]
	v_lshlrev_b64 v[100:101], 7, v[100:101]
	v_lshlrev_b64 v[108:109], 7, v[108:109]
	s_lshl_b64 s[20:21], s[20:21], 13
	v_lshl_add_u64 v[0:1], v[34:35], 0, v[0:1]
	v_lshl_add_u64 v[16:17], v[34:35], 0, v[16:17]
	v_lshl_add_u64 v[24:25], v[34:35], 0, v[24:25]
	v_lshl_add_u64 v[68:69], v[34:35], 0, v[68:69]
	v_lshl_add_u64 v[76:77], v[34:35], 0, v[76:77]
	v_lshl_add_u64 v[84:85], v[34:35], 0, v[84:85]
	v_lshl_add_u64 v[92:93], v[34:35], 0, v[92:93]
	v_lshl_add_u64 v[100:101], v[34:35], 0, v[100:101]
	v_lshl_add_u64 v[108:109], v[34:35], 0, v[108:109]
	v_lshl_add_u64 v[112:113], v[36:37], 0, s[20:21]
	v_readfirstlane_b32 s98, v170
	s_lshl_b32 s98, s98, 4
	s_add_i32 m0, s98, 0x0
	s_nop 0
	global_load_lds_dwordx4 v[0:1], off
	s_add_i32 m0, s98, 0x12000
	s_nop 0
	global_load_lds_dwordx4 v[8:9], off
	s_add_i32 m0, s98, 0x2000
	s_nop 0
	global_load_lds_dwordx4 v[16:17], off
	s_add_i32 m0, s98, 0x14000
	s_nop 0
	global_load_lds_dwordx4 v[20:21], off
	s_add_i32 m0, s98, 0x4000
	s_nop 0
	global_load_lds_dwordx4 v[24:25], off
	s_add_i32 m0, s98, 0x16000
	s_nop 0
	global_load_lds_dwordx4 v[64:65], off
	s_add_i32 m0, s98, 0x6000
	s_nop 0
	global_load_lds_dwordx4 v[68:69], off
	s_add_i32 m0, s98, 0x18000
	s_nop 0
	global_load_lds_dwordx4 v[72:73], off
	s_add_i32 m0, s98, 0x8000
	s_nop 0
	global_load_lds_dwordx4 v[76:77], off
	s_add_i32 m0, s98, 0x1a000
	s_nop 0
	global_load_lds_dwordx4 v[80:81], off
	s_add_i32 m0, s98, 0xa000
	s_nop 0
	global_load_lds_dwordx4 v[84:85], off
	s_add_i32 m0, s98, 0x1c000
	s_nop 0
	global_load_lds_dwordx4 v[88:89], off
	s_add_i32 m0, s98, 0xc000
	s_nop 0
	global_load_lds_dwordx4 v[92:93], off
	s_add_i32 m0, s98, 0x1e000
	s_nop 0
	global_load_lds_dwordx4 v[96:97], off
	s_add_i32 m0, s98, 0xe000
	s_nop 0
	global_load_lds_dwordx4 v[100:101], off
	s_add_i32 m0, s98, 0x20000
	s_nop 0
	global_load_lds_dwordx4 v[104:105], off
	s_add_i32 m0, s98, 0x10000
	s_nop 0
	global_load_lds_dwordx4 v[108:109], off
	s_add_i32 m0, s98, 0x22000
	s_nop 0
	global_load_lds_dwordx4 v[112:113], off
	s_max_i32 s16, s45, 4
	s_add_i32 s16, s16, -4
	s_min_u32 s20, s16, 24
	s_sub_i32 s16, s20, s39
	s_lshl_b32 s16, s16, 13
	s_sub_i32 s20, s20, s45
	s_mulk_i32 s20, 0x7c
	s_add_i32 s20, s20, 0
	s_add_i32 s20, s20, 0x24000
	v_lshl_add_u32 v118, v58, 2, s20
	v_lshl_add_u32 v119, v60, 2, s20
	s_waitcnt vmcnt(18)
	s_and_saveexec_b64 s[98:99], s[0:1]
	v_mul_f32_e32 v241, 0x3fb8aa3b, v241
	ds_write_b32 v42, v241
	s_or_b64 exec, exec, s[98:99]
	s_waitcnt vmcnt(0)
	v_add_u32_e32 v8, s16, v61
	v_add_u32_e32 v63, v8, v39
	s_waitcnt lgkmcnt(0)
	s_barrier
	s_and_saveexec_b64 s[98:99], s[58:59]
	s_cbranch_execz .Lattn_pf_b
	v_mov_b32_e32 v243, 1
	global_atomic_add v242, v31, v243, s[14:15] sc0
